# P0 rmsnorm rows loop: two rows prefetched ahead (third register set), no full vmcnt drain at loop top
# speedup vs baseline: 1.0126x; 1.0126x over previous
.LBB0_41:
	v_mbcnt_lo_u32_b32 v18, -1, 0
	v_mbcnt_hi_u32_b32 v18, -1, v18
	v_and_b32_e32 v19, 64, v18
	v_add_u32_e32 v19, 64, v19
	v_xor_b32_e32 v20, 1, v18
	v_cmp_lt_i32_e32 vcc, v20, v19
	v_readlane_b32 s36, v254, 4
	v_readlane_b32 s40, v254, 8
	v_cndmask_b32_e32 v20, v18, v20, vcc
	v_lshlrev_b32_e32 v188, 2, v20
	v_xor_b32_e32 v20, 2, v18
	v_cmp_lt_i32_e32 vcc, v20, v19
	v_readlane_b32 s50, v254, 18
	v_readlane_b32 s41, v254, 9
	v_cndmask_b32_e32 v20, v18, v20, vcc
	v_lshlrev_b32_e32 v189, 2, v20
	v_xor_b32_e32 v20, 4, v18
	v_cmp_lt_i32_e32 vcc, v20, v19
	v_readlane_b32 s51, v254, 19
	s_add_u32 s40, s50, 0x8520400
	v_cndmask_b32_e32 v20, v18, v20, vcc
	v_lshlrev_b32_e32 v190, 2, v20
	v_xor_b32_e32 v20, 8, v18
	v_cmp_lt_i32_e32 vcc, v20, v19
	v_readlane_b32 s42, v254, 10
	s_addc_u32 s41, s51, 0
	v_cndmask_b32_e32 v20, v18, v20, vcc
	v_lshlrev_b32_e32 v191, 2, v20
	v_xor_b32_e32 v20, 16, v18
	v_cmp_lt_i32_e32 vcc, v20, v19
	v_readlane_b32 s43, v254, 11
	s_add_u32 s42, s50, 0x8220000
	v_cndmask_b32_e32 v20, v18, v20, vcc
	v_lshlrev_b32_e32 v192, 2, v20
	v_xor_b32_e32 v20, 32, v18
	v_cmp_lt_i32_e32 vcc, v20, v19
	s_addc_u32 s43, s51, 0
	s_ashr_i32 s21, s20, 31
	v_cndmask_b32_e32 v18, v18, v20, vcc
	s_lshl_b64 s[0:1], s[20:21], 5
	v_mov_b32_e32 v179, 0
	v_lshlrev_b32_e32 v193, 2, v18
	v_lshl_add_u32 v18, v1, 4, 0
	v_lshl_add_u64 v[74:75], s[0:1], 0, v[178:179]
	s_mov_b64 s[0:1], 0xda00000
	v_add_u32_e32 v142, 0x12000, v18
	v_lshl_add_u64 v[182:183], v[74:75], 0, s[0:1]
	ds_read_b128 v[18:21], v142
	ds_read_b128 v[22:25], v142 offset:1024
	ds_read_b128 v[26:29], v142 offset:2048
	ds_read_b128 v[30:33], v142 offset:3072
	ds_read_b128 v[34:37], v142 offset:4096
	ds_read_b128 v[38:41], v142 offset:5120
	ds_read_b128 v[42:45], v142 offset:6144
	ds_read_b128 v[46:49], v142 offset:7168
	ds_read_b128 v[50:53], v142 offset:8192
	ds_read_b128 v[54:57], v142 offset:9216
	ds_read_b128 v[58:61], v142 offset:10240
	ds_read_b128 v[62:65], v142 offset:11264
	ds_read_b128 v[66:69], v142 offset:12288
	ds_read_b128 v[70:73], v142 offset:13312
	ds_read_b128 v[74:77], v142 offset:14336
	ds_read_b128 v[78:81], v142 offset:15360
	ds_read_b128 v[82:85], v142 offset:16384
	ds_read_b128 v[86:89], v142 offset:17408
	ds_read_b128 v[90:93], v142 offset:18432
	ds_read_b128 v[94:97], v142 offset:19456
	ds_read_b128 v[98:101], v142 offset:20480
	ds_read_b128 v[102:105], v142 offset:21504
	ds_read_b128 v[106:109], v142 offset:22528
	ds_read_b128 v[110:113], v142 offset:23552
	ds_read_b128 v[114:117], v142 offset:24576
	ds_read_b128 v[118:121], v142 offset:25600
	ds_read_b128 v[122:125], v142 offset:26624
	ds_read_b128 v[126:129], v142 offset:27648
	ds_read_b128 v[130:133], v142 offset:28672
	ds_read_b128 v[134:137], v142 offset:29696
	ds_read_b128 v[138:141], v142 offset:30720
	ds_read_b128 v[142:145], v142 offset:31744
	v_readlane_b32 s44, v254, 12
	v_readlane_b32 s45, v254, 13
	v_readlane_b32 s46, v254, 14
	v_readlane_b32 s47, v254, 15
	v_readlane_b32 s48, v254, 16
	v_readlane_b32 s49, v254, 17
	s_lshl_b64 s[0:1], s[20:21], 11
	s_mov_b32 s25, 0
	v_cmp_gt_u32_e64 s[2:3], 8, v1
	v_cmp_eq_u32_e64 s[4:5], 7, v1
	v_cmp_eq_u32_e64 s[6:7], 6, v1
	v_cmp_eq_u32_e64 s[8:9], 5, v1
	v_cmp_eq_u32_e64 s[10:11], 4, v1
	v_cmp_eq_u32_e64 s[12:13], 3, v1
	v_cmp_eq_u32_e64 s[14:15], 2, v1
	v_cmp_eq_u32_e64 s[16:17], 1, v1
	v_cmp_eq_u32_e64 s[18:19], 0, v1
	v_lshl_or_b32 v184, v1, 3, s0
	v_mov_b32_e32 v185, s1
	v_mov_b32_e32 v179, 0x358637bd
	s_mov_b32 s21, 0xf800000
	v_mov_b32_e32 v194, 0x260
	s_movk_i32 s44, 0x7fff
	s_mov_b32 s45, 0xc00000
	s_mov_b32 s46, 0xbfb8aa3b
	s_mov_b32 s47, 0x3f2aaaab
	v_mov_b32_e32 v195, 0x3ecc95a3
	s_mov_b32 s48, 0x3f317218
	s_mov_b32 s49, 0x7f800000
	s_mov_b32 s50, 0x33800000
	s_mov_b64 s[26:27], 0x10000
	s_mov_b64 s[28:29], 0x400000
	v_mov_b32_e32 v196, 1
	v_mov_b32_e32 v197, 0x7f800000
	v_mov_b32_e32 v198, 0x7fc00000
	s_mov_b32 s51, s20
	v_mov_b32_e32 v199, 0xff800000
	v_readlane_b32 s37, v254, 5
	v_readlane_b32 s38, v254, 6
	v_readlane_b32 s39, v254, 7
	s_add_i32 s38, s20, 0x800
	s_cmpk_gt_i32 s38, 0x40ff
	s_cbranch_scc0 .Lp0p_a1
	s_add_i32 s24, s38, 0xffffbf00
	s_lshl_b64 s[36:37], s[24:25], 12
	s_add_u32 s36, s58, s36
	s_addc_u32 s37, s59, s37
	s_branch .Lp0p_a9
.Lp0p_a1:
	s_cmpk_gt_i32 s38, 0x207f
	s_cselect_b32 s52, 0xffffdf80, 0
	s_cselect_b32 s53, 0x2000, 0
	s_add_i32 s52, s52, s38
	s_cmpk_lt_i32 s52, 0x80
	s_cbranch_scc0 .Lp0p_a2
	s_add_i32 s24, s52, 0xffffff90
	s_lshl_b64 s[36:37], s[24:25], 12
	s_add_u32 s36, s70, s36
	s_addc_u32 s37, s71, s37
	s_cmpk_gt_i32 s52, 0x6f
	s_cselect_b32 s37, s37, 0
	s_cselect_b32 s36, s36, 0
	s_branch .Lp0p_a9
.Lp0p_a2:
	s_add_i32 s24, s52, s53
	s_add_i32 s24, s24, 0xffffff80
	s_lshl_b64 s[36:37], s[24:25], 12
	s_add_u32 s36, s56, s36
	s_addc_u32 s37, s57, s37
.Lp0p_a9:
	s_mov_b64 s[100:101], s[36:37]
	s_cmp_eq_u64 s[36:37], 0
	s_cbranch_scc1 .Lp0p_z
	global_load_dwordx4 v[238:241], v180, s[36:37]
	global_load_dwordx4 v[234:237], v180, s[36:37] offset:1024
	global_load_dwordx4 v[246:249], v180, s[36:37] offset:2048
	global_load_dwordx4 v[242:245], v180, s[36:37] offset:3072
	s_branch .Lp0p_j
.Lp0p_z:
	v_mov_b32_e32 v238, 0
	v_mov_b32_e32 v239, 0
	v_mov_b32_e32 v240, 0
	v_mov_b32_e32 v241, 0
	v_mov_b32_e32 v234, 0
	v_mov_b32_e32 v235, 0
	v_mov_b32_e32 v236, 0
	v_mov_b32_e32 v237, 0
	v_mov_b32_e32 v246, 0
	v_mov_b32_e32 v247, 0
	v_mov_b32_e32 v248, 0
	v_mov_b32_e32 v249, 0
	v_mov_b32_e32 v242, 0
	v_mov_b32_e32 v243, 0
	v_mov_b32_e32 v244, 0
	v_mov_b32_e32 v245, 0
.Lp0p_j:
	s_waitcnt vmcnt(0)
	s_branch .LBB0_43
.LBB0_42:
	s_or_b64 exec, exec, s[0:1]
	v_lshl_add_u64 v[182:183], v[182:183], 0, s[26:27]
	v_lshl_add_u64 v[184:185], v[184:185], 0, s[28:29]
	s_and_b64 vcc, exec, s[34:35]
	s_mov_b64 s[22:23], s[100:101]
	s_mov_b64 s[100:101], s[36:37]
	s_waitcnt vmcnt(10) lgkmcnt(0)
	s_bitcmp1_b32 s51, 11
	s_cbranch_scc1 .Lp0_cpA
	v_mov_b32_e32 v170, v238
	v_mov_b32_e32 v171, v239
	v_mov_b32_e32 v172, v240
	v_mov_b32_e32 v173, v241
	v_mov_b32_e32 v162, v234
	v_mov_b32_e32 v163, v235
	v_mov_b32_e32 v164, v236
	v_mov_b32_e32 v165, v237
	v_mov_b32_e32 v174, v246
	v_mov_b32_e32 v175, v247
	v_mov_b32_e32 v176, v248
	v_mov_b32_e32 v177, v249
	v_mov_b32_e32 v166, v242
	v_mov_b32_e32 v167, v243
	v_mov_b32_e32 v168, v244
	v_mov_b32_e32 v169, v245
	s_branch .Lp0_cpd
.Lp0_cpA:
	v_mov_b32_e32 v170, v150
	v_mov_b32_e32 v171, v151
	v_mov_b32_e32 v172, v152
	v_mov_b32_e32 v173, v153
	v_mov_b32_e32 v162, v146
	v_mov_b32_e32 v163, v147
	v_mov_b32_e32 v164, v148
	v_mov_b32_e32 v165, v149
	v_mov_b32_e32 v174, v158
	v_mov_b32_e32 v175, v159
	v_mov_b32_e32 v176, v160
	v_mov_b32_e32 v177, v161
	v_mov_b32_e32 v166, v154
	v_mov_b32_e32 v167, v155
	v_mov_b32_e32 v168, v156
	v_mov_b32_e32 v169, v157
.Lp0_cpd:
	s_addk_i32 s51, 0x800
	s_cbranch_vccnz .LBB0_66

.LBB0_47:
	s_cmpk_gt_i32 s51, 0x3aff
	s_cselect_b64 s[34:35], -1, 0
	s_mov_b64 s[36:37], 0
	s_cmpk_gt_i32 s51, 0x32ff
	s_cbranch_scc1 .LBB0_63
	s_add_i32 s38, s51, 0x1000
	s_cmpk_gt_i32 s38, 0x40ff
	s_cbranch_scc0 .Lp0t_a1
	s_add_i32 s24, s38, 0xffffbf00
	s_lshl_b64 s[36:37], s[24:25], 12
	s_add_u32 s36, s58, s36
	s_addc_u32 s37, s59, s37
	s_branch .Lp0t_a9

.Lp0t_a9:
	s_bitcmp1_b32 s51, 11
	s_cbranch_scc1 .Lp0_ldB
	s_cmp_eq_u64 s[36:37], 0
	s_cbranch_scc1 .Lp0ta_z
	global_load_dwordx4 v[150:153], v180, s[36:37]
	global_load_dwordx4 v[146:149], v180, s[36:37] offset:1024
	global_load_dwordx4 v[158:161], v180, s[36:37] offset:2048
	global_load_dwordx4 v[154:157], v180, s[36:37] offset:3072
	s_branch .LBB0_63
.Lp0ta_z:
	v_mov_b32_e32 v150, 0
	v_mov_b32_e32 v151, 0
	v_mov_b32_e32 v152, 0
	v_mov_b32_e32 v153, 0
	v_mov_b32_e32 v146, 0
	v_mov_b32_e32 v147, 0
	v_mov_b32_e32 v148, 0
	v_mov_b32_e32 v149, 0
	v_mov_b32_e32 v158, 0
	v_mov_b32_e32 v159, 0
	v_mov_b32_e32 v160, 0
	v_mov_b32_e32 v161, 0
	v_mov_b32_e32 v154, 0
	v_mov_b32_e32 v155, 0
	v_mov_b32_e32 v156, 0
	v_mov_b32_e32 v157, 0
	s_branch .LBB0_63
.Lp0_ldB:
	s_cmp_eq_u64 s[36:37], 0
	s_cbranch_scc1 .Lp0tb_z
	global_load_dwordx4 v[238:241], v180, s[36:37]
	global_load_dwordx4 v[234:237], v180, s[36:37] offset:1024
	global_load_dwordx4 v[246:249], v180, s[36:37] offset:2048
	global_load_dwordx4 v[242:245], v180, s[36:37] offset:3072
	s_branch .LBB0_63

.Lpost_getpc1:
	s_add_u32 s98, s98, (.LBB0_930-.Lpost_getpc1)&4294967295
	s_addc_u32 s99, s99, (.LBB0_930-.Lpost_getpc1)>>32
	s_setpc_b64 s[98:99]
	s_nop 0
	s_nop 0
	s_nop 0
	s_nop 0
	s_nop 0
	s_nop 0
	s_nop 0
	s_nop 0
	s_nop 0
	s_nop 0
	s_nop 0
	s_nop 0
	s_nop 0
	s_nop 0
	s_nop 0
	s_nop 0
	s_nop 0
	s_nop 0
	s_nop 0
	s_nop 0
	s_nop 0
	s_nop 0
	s_nop 0
	s_nop 0
	s_nop 0
	s_nop 0
	s_nop 0
	s_nop 0
	s_nop 0
	s_nop 0
	s_nop 0
	s_nop 0
	s_nop 0
	s_nop 0
	s_nop 0
	s_nop 0
	s_nop 0
	s_nop 0
	s_nop 0
	s_nop 0
	s_nop 0
	s_nop 0
	s_nop 0
	s_nop 0
	s_nop 0
	s_nop 0
	s_nop 0
	s_nop 0
	s_nop 0
	s_nop 0
	s_nop 0
	s_nop 0
	s_nop 0
	s_nop 0
.LBB0_124:
	v_mov_b32_e32 v14, v0
	s_cmp_gt_i32 s95, -1
	v_readfirstlane_b32 s2, v14
	s_cbranch_scc0 .LBB0_126
	s_lshl_b32 s4, s95, 7
	s_cbranch_execz .LBB0_127
	s_branch .LBB0_128
